# tail-fill weight conversion: P0 converts only the weights needed first (31 pct of items); workgroups idle in the last partial round of the P2/P5/P11/P14/P17 GEMM phases convert the rest before the gri
# speedup vs baseline: 1.0099x; 1.0099x over previous
.LBB0_36:
	s_lshl_b32 s0, s24, 3
	s_add_i32 s98, s25, s0
	s_lshl_b32 s99, s33, 3
	s_mov_b32 s100, 0x13a80
	s_cmpk_eq_i32 s33, 0x100
	s_cselect_b32 s100, 0x6180, s100
	s_mov_b32 s101, 0
.Lmy_cvt_entry:
	v_mbcnt_lo_u32_b32 v100, -1, 0
	v_mbcnt_hi_u32_b32 v100, -1, v100
	s_cmp_ge_i32 s98, s100
	s_cbranch_scc1 .Lmy_cvt_done
	s_mul_i32 s0, s25, 0x2100
	v_ashrrev_i32_e32 v1, 3, v100
	v_and_b32_e32 v113, 7, v100
	s_add_i32 s6, s0, 0
	v_mul_u32_u24_e32 v2, 0x420, v113
	v_lshlrev_b32_e32 v3, 2, v1
	v_add3_u32 v122, s6, v2, v3
	v_ashrrev_i32_e32 v2, 5, v100
	s_movk_i32 s3, 0x6040
	v_add_u32_e32 v8, 18, v2
	v_mad_i64_i32 v[54:55], s[8:9], v8, s3, 0
	v_add_u32_e32 v8, 20, v2
	v_mad_i64_i32 v[56:57], s[8:9], v8, s3, 0
	v_add_u32_e32 v8, 22, v2
	s_movk_i32 s10, 0x84
	v_add_u32_e32 v4, 2, v2
	v_add_u32_e32 v5, 6, v2
	v_add_u32_e32 v6, 10, v2
	v_add_u32_e32 v7, 14, v2
	v_mad_i64_i32 v[58:59], s[8:9], v8, s3, 0
	v_add_u32_e32 v8, 24, v2
	v_mad_i64_i32 v[36:37], s[8:9], v2, s3, 0
	v_mul_lo_u32 v126, v2, s10
	v_mad_i64_i32 v[38:39], s[8:9], v4, s3, 0
	v_add_u32_e32 v4, 4, v2
	v_mad_i64_i32 v[42:43], s[8:9], v5, s3, 0
	v_add_u32_e32 v5, 8, v2
	v_mad_i64_i32 v[46:47], s[8:9], v6, s3, 0
	v_add_u32_e32 v6, 12, v2
	v_mad_i64_i32 v[50:51], s[8:9], v7, s3, 0
	v_add_u32_e32 v7, 16, v2
	v_mad_i64_i32 v[60:61], s[8:9], v8, s3, 0
	v_add_u32_e32 v8, 26, v2
	v_add_u32_e32 v9, 28, v2
	v_add_u32_e32 v10, 30, v2
	v_add_u32_e32 v11, 32, v2
	v_add_u32_e32 v12, 34, v2
	v_add_u32_e32 v13, 36, v2
	v_add_u32_e32 v14, 38, v2
	v_add_u32_e32 v15, 40, v2
	v_add_u32_e32 v16, 42, v2
	v_add_u32_e32 v17, 44, v2
	v_add_u32_e32 v18, 46, v2
	v_add_u32_e32 v19, 48, v2
	v_add_u32_e32 v20, 50, v2
	v_add_u32_e32 v21, 52, v2
	v_add_u32_e32 v22, 54, v2
	v_add_u32_e32 v23, 56, v2
	v_add_u32_e32 v24, 58, v2
	v_add_u32_e32 v25, 60, v2
	v_add_u32_e32 v26, 62, v2
	v_lshlrev_b32_e32 v2, 3, v100
	v_and_b32_e32 v27, 56, v2
	v_mov_b32_e32 v35, 0
	v_lshlrev_b32_e32 v34, 4, v113
	v_mad_i64_i32 v[40:41], s[8:9], v4, s3, 0
	v_mad_i64_i32 v[44:45], s[8:9], v5, s3, 0
	v_mad_i64_i32 v[48:49], s[8:9], v6, s3, 0
	v_mad_i64_i32 v[52:53], s[8:9], v7, s3, 0
	v_mul_u32_u24_e32 v2, 0x84, v27
	s_lshl_b32 s12, s33, 3
	v_add3_u32 v127, s6, v2, v3
	v_lshl_add_u64 v[2:3], s[28:29], 0, v[34:35]
	s_mov_b64 s[8:9], 0x15900000
	s_add_u32 s13, s28, 0x15a00000
	v_lshl_add_u64 v[62:63], v[2:3], 0, s[8:9]
	s_mov_b64 s[8:9], 0x15700000
	s_addc_u32 s14, s29, 0
	v_lshl_add_u64 v[64:65], v[2:3], 0, s[8:9]
	s_mov_b64 s[8:9], 0x14f00000
	s_add_u32 s15, s28, 0xcc00000
	v_lshl_add_u64 v[66:67], v[2:3], 0, s[8:9]
	s_mov_b64 s[8:9], 0x14300000
	s_addc_u32 s16, s29, 0
	v_add_u32_e32 v115, s6, v34
	v_lshl_add_u64 v[68:69], v[2:3], 0, s[8:9]
	s_mov_b64 s[8:9], 0x13b00000
	v_lshlrev_b32_e32 v34, 1, v27
	s_add_u32 s17, s28, 0x2000000
	v_and_b32_e32 v123, 31, v100
	v_lshl_add_u64 v[70:71], v[2:3], 0, s[8:9]
	v_lshl_add_u64 v[2:3], s[28:29], 0, v[34:35]
	s_mov_b64 s[8:9], 0x12200000
	s_addc_u32 s18, s29, 0
	v_lshl_add_u32 v125, v123, 2, s6
	v_lshl_add_u64 v[72:73], v[2:3], 0, s[8:9]
	s_lshl_b32 s6, s24, 7
	s_lshl_b32 s8, s25, 4
	v_add_u32_e32 v4, 0x210, v126
	v_add_u32_e32 v5, 0x420, v126
	v_add_u32_e32 v6, 0x630, v126
	v_add_u32_e32 v7, 0x840, v126
	s_add_i32 s20, s6, s8
	s_lshl_b32 s6, s24, 8
	s_lshl_b32 s8, s25, 5
	s_mov_b32 s7, 0
	v_mul_lo_u32 v118, v1, s10
	v_add_u32_e32 v119, 8, v1
	v_add_u32_e32 v120, 16, v1
	v_add_u32_e32 v121, 24, v1
	v_cmp_gt_u32_e64 s[0:1], 4, v113
	v_add_u32_e32 v124, 60, v113
	s_add_i32 s19, s2, 0xfffec680
	s_lshl_b32 s21, s33, 7
	s_add_i32 s22, s6, s8
	s_lshl_b32 s23, s33, 8
	s_add_i32 s80, s2, 0xffff5400
	s_mov_b32 s81, 0x10000
	s_mov_b32 s82, 0x18000
	s_mov_b32 s83, 0x20000
	s_mov_b32 s84, 0x30000
	s_mov_b32 s85, 0x40000
	s_mov_b32 s86, 0x50000
	s_mov_b32 s87, 0x60000
	s_mov_b32 s88, 0x70000
	v_add_u32_e32 v128, v125, v4
	v_add_u32_e32 v129, v125, v6
	s_movk_i32 s89, 0x2b00
	v_add_u32_e32 v130, v125, v5
	v_add_u32_e32 v131, v125, v7
	v_mad_i64_i32 v[74:75], s[8:9], v8, s3, 0
	v_mad_i64_i32 v[76:77], s[8:9], v9, s3, 0
	v_mad_i64_i32 v[78:79], s[8:9], v10, s3, 0
	v_mad_i64_i32 v[80:81], s[8:9], v11, s3, 0
	v_mad_i64_i32 v[82:83], s[8:9], v12, s3, 0
	v_mad_i64_i32 v[84:85], s[8:9], v13, s3, 0
	v_mad_i64_i32 v[86:87], s[8:9], v14, s3, 0
	v_mad_i64_i32 v[88:89], s[8:9], v15, s3, 0
	v_mad_i64_i32 v[90:91], s[8:9], v16, s3, 0
	v_mad_i64_i32 v[92:93], s[8:9], v17, s3, 0
	v_mad_i64_i32 v[94:95], s[8:9], v18, s3, 0
	v_mad_i64_i32 v[96:97], s[8:9], v19, s3, 0
	v_mad_i64_i32 v[98:99], s[8:9], v20, s3, 0
	v_mad_i64_i32 v[100:101], s[8:9], v21, s3, 0
	v_mad_i64_i32 v[102:103], s[8:9], v22, s3, 0
	v_mad_i64_i32 v[104:105], s[8:9], v23, s3, 0
	v_mad_i64_i32 v[106:107], s[8:9], v24, s3, 0
	v_mad_i64_i32 v[108:109], s[8:9], v25, s3, 0
	v_mad_i64_i32 v[110:111], s[2:3], v26, s3, 0
	v_lshlrev_b32_e32 v112, 2, v113
	v_lshlrev_b32_e32 v114, 3, v113
	s_branch .LBB0_40

.LBB0_39:
	s_add_i32 s98, s98, s99
	s_cmp_lt_i32 s98, s100
	s_cbranch_scc0 .Lmy_cvt_done
.LBB0_40:
	s_mov_b32 s90, 0
	s_cmp_ge_u32 s98, 0x2b00
	s_cselect_b32 s90, 0x8100, s90
	s_cmp_ge_u32 s98, 0x4080
	s_cselect_b32 s90, 0xc180, s90
	s_cmp_ge_u32 s98, 0x6180
	s_cselect_b32 s90, 0xffffc980, s90
	s_cmp_ge_u32 s98, 0x8c80
	s_cselect_b32 s90, 0x3500, s90
	s_cmp_ge_u32 s98, 0xa200
	s_cselect_b32 s90, 0xffffb400, s90
	s_cmp_ge_u32 s98, 0xcd00
	s_cselect_b32 s90, 0xa00, s90
	s_cmp_ge_u32 s98, 0xe280
	s_cselect_b32 s90, 0x4080, s90
	s_cmp_ge_u32 s98, 0xee80
	s_cselect_b32 s90, 0x4880, s90
	s_cmp_ge_u32 s98, 0xf200
	s_cselect_b32 s90, 0x3d00, s90
	s_cmp_ge_u32 s98, 0xfa00
	s_cselect_b32 s90, 0xffff8700, s90
	s_cmp_ge_u32 s98, 0x12500
	s_cselect_b32 s90, 0xffffc780, s90
	s_add_i32 s90, s90, s98
	s_add_i32 s19, s90, 0xfffec680
	s_lshl_b32 s20, s90, 4
	s_lshl_b32 s22, s90, 5
	s_add_i32 s80, s90, 0xffff5400
	s_cmp_gt_i32 s90, 0xabff
	s_mov_b64 s[2:3], -1
	s_cbranch_scc0 .LBB0_134
	s_cmp_gt_u32 s90, 0x101ff
	s_cbranch_scc0 .LBB0_115
	s_cmp_gt_u32 s90, 0x11aff
	s_cbranch_scc0 .LBB0_80
	s_cmp_gt_u32 s90, 0x122ff
	s_cbranch_scc0 .LBB0_77
	s_cmp_gt_u32 s90, 0x12eff
	s_cbranch_scc0 .LBB0_58
	s_cmp_gt_u32 s90, 0x136ff
	s_cbranch_scc0 .LBB0_55
	s_cmp_gt_u32 s90, 0x1387f
	s_cbranch_scc0 .LBB0_52
	s_cmp_gt_u32 s90, 0x1397f
	s_cbranch_scc0 .LBB0_49
	s_lshr_b32 s2, s19, 3
	s_bfe_u32 s3, s19, 0x30003
	v_readlane_b32 s52, v252, 18
	s_bitcmp0_b32 s90, 6
	v_readlane_b32 s60, v252, 26
	v_readlane_b32 s61, v252, 27
	v_readlane_b32 s64, v252, 30
	v_readlane_b32 s65, v252, 31
	s_cselect_b32 s10, s61, s65
	s_cselect_b32 s11, s60, s64
	s_lshr_b32 s6, s19, 4
	s_and_b32 s6, s6, 0xffffff8
	s_or_b32 s6, s6, s3
	s_lshl_b64 s[8:9], s[6:7], 16
	s_add_u32 s8, s11, s8
	s_mov_b32 s3, s7
	s_addc_u32 s9, s10, s9
	s_lshl_b64 s[2:3], s[2:3], 15
	s_add_u32 s2, s13, s2
	s_addc_u32 s3, s14, s3
	s_and_b32 s10, s20, 64
	v_add_u32_e32 v2, s10, v1
	v_ashrrev_i32_e32 v3, 31, v2
	s_and_b32 s11, s22, 0x60
	v_lshlrev_b64 v[2:3], 9, v[2:3]
	v_lshl_add_u64 v[2:3], s[8:9], 0, v[2:3]
	s_lshl_b32 s6, s11, 2
	v_lshl_add_u64 v[2:3], v[2:3], 0, s[6:7]
	v_lshlrev_b32_e32 v34, 2, v112
	v_lshl_add_u64 v[30:31], v[2:3], 0, v[34:35]
	s_movk_i32 s6, 0x2000
	v_add_co_u32_e32 v10, vcc, s6, v30
	s_movk_i32 s6, 0x4000
	s_nop 0
	v_addc_co_u32_e32 v11, vcc, 0, v31, vcc
	v_add_co_u32_e32 v18, vcc, s6, v30
	s_movk_i32 s6, 0x6000
	s_nop 0
	v_addc_co_u32_e32 v19, vcc, 0, v31, vcc
	v_add_co_u32_e32 v26, vcc, s6, v30
	global_load_dwordx4 v[2:5], v[30:31], off
	s_nop 0
	v_addc_co_u32_e32 v27, vcc, 0, v31, vcc
	global_load_dwordx4 v[6:9], v[10:11], off offset:-4096
	s_nop 0
	global_load_dwordx4 v[10:13], v[10:11], off
	s_nop 0
	global_load_dwordx4 v[14:17], v[18:19], off offset:-4096
	s_nop 0
	global_load_dwordx4 v[18:21], v[18:19], off
	s_nop 0
	global_load_dwordx4 v[22:25], v[26:27], off offset:-4096
	s_nop 0
	global_load_dwordx4 v[26:29], v[26:27], off
	s_movk_i32 s6, 0x7000
	v_add_co_u32_e32 v30, vcc, s6, v30
	v_add_u32_e32 v134, v115, v118
	s_nop 0
	v_addc_co_u32_e32 v31, vcc, 0, v31, vcc
	global_load_dwordx4 v[30:33], v[30:31], off
	v_add_u32_e32 v135, 0x420, v134
	v_add_u32_e32 v136, 0x428, v134
	v_add_u32_e32 v137, 0x840, v134
	v_add_u32_e32 v138, 0x848, v134
	v_add_u32_e32 v139, 0xc60, v134
	v_add_u32_e32 v140, 0xc68, v134
	v_add_u32_e32 v141, 0x1080, v134
	v_add_u32_e32 v142, 0x1088, v134
	v_add_u32_e32 v143, 0x14a0, v134
	v_add_u32_e32 v144, 0x14a8, v134
	v_add_u32_e32 v145, 0x18c0, v134
	v_add_u32_e32 v146, 0x18c8, v134
	v_add_u32_e32 v147, 0x1ce0, v134
	v_add_u32_e32 v148, 0x1ce8, v134
	s_lshl_b32 s6, s10, 1
	v_add_u32_e32 v116, s11, v1
	s_add_u32 s2, s2, s6
	v_ashrrev_i32_e32 v117, 31, v116
	s_addc_u32 s3, s3, 0
	v_lshlrev_b32_e32 v34, 1, v114
	v_lshlrev_b64 v[116:117], 8, v[116:117]
	v_lshl_add_u64 v[132:133], s[2:3], 0, v[34:35]
	v_readlane_b32 s53, v252, 19
	v_readlane_b32 s54, v252, 20
	v_readlane_b32 s55, v252, 21
	v_readlane_b32 s56, v252, 22
	v_readlane_b32 s57, v252, 23
	v_readlane_b32 s58, v252, 24
	v_readlane_b32 s59, v252, 25
	v_readlane_b32 s62, v252, 28
	v_readlane_b32 s63, v252, 29
	v_readlane_b32 s66, v252, 32
	v_readlane_b32 s67, v252, 33
	s_mov_b64 s[2:3], 0
	s_waitcnt vmcnt(7)
	ds_write2_b32 v134, v2, v3 offset1:1
	ds_write2_b32 v134, v4, v5 offset0:2 offset1:3
	s_waitcnt vmcnt(6)
	ds_write2_b32 v135, v6, v7 offset1:1
	ds_write2_b32 v136, v8, v9 offset1:1
	s_waitcnt vmcnt(5)
	ds_write2_b32 v137, v10, v11 offset1:1
	ds_write2_b32 v138, v12, v13 offset1:1
	s_waitcnt vmcnt(4)
	ds_write2_b32 v139, v14, v15 offset1:1
	ds_write2_b32 v140, v16, v17 offset1:1
	s_waitcnt vmcnt(3)
	ds_write2_b32 v141, v18, v19 offset1:1
	ds_write2_b32 v142, v20, v21 offset1:1
	s_waitcnt vmcnt(2)
	ds_write2_b32 v143, v22, v23 offset1:1
	ds_write2_b32 v144, v24, v25 offset1:1
	s_waitcnt vmcnt(1)
	ds_write2_b32 v145, v26, v27 offset1:1
	ds_write2_b32 v146, v28, v29 offset1:1
	s_waitcnt vmcnt(0)
	ds_write2_b32 v147, v30, v31 offset1:1
	ds_write2_b32 v148, v32, v33 offset1:1
	s_waitcnt lgkmcnt(0)
	ds_read2_b32 v[6:7], v122 offset0:33 offset1:41
	ds_read2_b32 v[8:9], v122 offset1:8
	ds_read2_b32 v[10:11], v122 offset0:66 offset1:74
	ds_read2_b32 v[12:13], v122 offset0:99 offset1:107
	ds_read2_b32 v[14:15], v122 offset0:132 offset1:140
	ds_read2_b32 v[16:17], v122 offset0:165 offset1:173
	ds_read2_b32 v[18:19], v122 offset0:198 offset1:206
	ds_read2_b32 v[20:21], v122 offset0:231 offset1:239
	v_lshl_add_u64 v[22:23], v[132:133], 0, v[116:117]
	s_waitcnt lgkmcnt(6)
	v_cvt_pk_bf16_f32 v2, v8, v6
	s_waitcnt lgkmcnt(4)
	v_cvt_pk_bf16_f32 v3, v10, v12
	s_waitcnt lgkmcnt(2)
	v_cvt_pk_bf16_f32 v4, v14, v16
	s_waitcnt lgkmcnt(0)
	v_cvt_pk_bf16_f32 v5, v18, v20
	global_store_dwordx4 v[22:23], v[2:5], off
	v_cvt_pk_bf16_f32 v6, v9, v7
	v_cvt_pk_bf16_f32 v7, v11, v13
	v_add_u32_e32 v2, s11, v119
	v_ashrrev_i32_e32 v3, 31, v2
	v_cvt_pk_bf16_f32 v8, v15, v17
	v_cvt_pk_bf16_f32 v9, v19, v21
	v_lshlrev_b64 v[2:3], 8, v[2:3]
	ds_read2_b32 v[10:11], v122 offset0:49 offset1:57
	ds_read2_b32 v[12:13], v122 offset0:16 offset1:24
	ds_read2_b32 v[14:15], v122 offset0:82 offset1:90
	ds_read2_b32 v[16:17], v122 offset0:115 offset1:123
	ds_read2_b32 v[18:19], v122 offset0:148 offset1:156
	ds_read2_b32 v[20:21], v122 offset0:181 offset1:189
	ds_read2_b32 v[22:23], v122 offset0:214 offset1:222
	ds_read2_b32 v[24:25], v122 offset0:247 offset1:255
	v_lshl_add_u64 v[2:3], v[132:133], 0, v[2:3]
	global_store_dwordx4 v[2:3], v[6:9], off
	s_waitcnt lgkmcnt(6)
	v_cvt_pk_bf16_f32 v2, v12, v10
	s_waitcnt lgkmcnt(4)
	v_cvt_pk_bf16_f32 v3, v14, v16
	v_add_u32_e32 v6, s11, v120
	v_ashrrev_i32_e32 v7, 31, v6
	v_lshlrev_b64 v[6:7], 8, v[6:7]
	s_waitcnt lgkmcnt(2)
	v_cvt_pk_bf16_f32 v4, v18, v20
	s_waitcnt lgkmcnt(0)
	v_cvt_pk_bf16_f32 v5, v22, v24
	v_lshl_add_u64 v[6:7], v[132:133], 0, v[6:7]
	global_store_dwordx4 v[6:7], v[2:5], off
	v_add_u32_e32 v6, s11, v121
	v_ashrrev_i32_e32 v7, 31, v6
	v_lshlrev_b64 v[6:7], 8, v[6:7]
	v_cvt_pk_bf16_f32 v2, v13, v11
	v_cvt_pk_bf16_f32 v3, v15, v17
	v_cvt_pk_bf16_f32 v4, v19, v21
	v_cvt_pk_bf16_f32 v5, v23, v25
	v_lshl_add_u64 v[6:7], v[132:133], 0, v[6:7]
	global_store_dwordx4 v[6:7], v[2:5], off
	s_waitcnt lgkmcnt(0)

.Lmy_cvt_done:
	s_cmp_eq_u32 s101, 0
	s_cbranch_scc1 .LBB0_151
	s_cmp_eq_u32 s101, 1
	s_cbranch_scc1 .Lmy_back_p2
	s_cmp_eq_u32 s101, 2
	s_cbranch_scc1 .Lmy_back_p5
	s_branch .Lmy_h1_back

.LBB0_302:
	s_cmpk_lg_i32 s33, 0x100
	s_cbranch_scc1 .Lmy_skip_p2
	s_cmp_lt_u32 s76, 108
	s_cbranch_scc1 .Lmy_skip_p2
	s_waitcnt vmcnt(0) lgkmcnt(0)
	s_barrier
	v_writelane_b32 v255, s0, 0
	v_writelane_b32 v255, s1, 1
	v_writelane_b32 v255, s2, 2
	v_writelane_b32 v255, s3, 3
	v_writelane_b32 v255, s4, 4
	v_writelane_b32 v255, s5, 5
	v_writelane_b32 v255, s6, 6
	v_writelane_b32 v255, s7, 7
	v_writelane_b32 v255, s8, 8
	v_writelane_b32 v255, s9, 9
	v_writelane_b32 v255, s10, 10
	v_writelane_b32 v255, s11, 11
	v_writelane_b32 v255, s12, 12
	v_writelane_b32 v255, s13, 13
	v_writelane_b32 v255, s14, 14
	v_writelane_b32 v255, s15, 15
	v_writelane_b32 v255, s16, 16
	v_writelane_b32 v255, s17, 17
	v_writelane_b32 v255, s18, 18
	v_writelane_b32 v255, s19, 19
	v_writelane_b32 v255, s20, 20
	v_writelane_b32 v255, s21, 21
	v_writelane_b32 v255, s22, 22
	v_writelane_b32 v255, s23, 23
	v_writelane_b32 v255, s26, 24
	v_writelane_b32 v255, s27, 25
	v_writelane_b32 v255, s34, 26
	v_writelane_b32 v255, s35, 27
	v_writelane_b32 v255, s36, 28
	v_writelane_b32 v255, s37, 29
	v_writelane_b32 v255, s38, 30
	v_writelane_b32 v255, s39, 31
	v_writelane_b32 v255, s40, 32
	v_writelane_b32 v255, s41, 33
	v_writelane_b32 v255, s42, 34
	v_writelane_b32 v255, s43, 35
	v_writelane_b32 v255, s44, 36
	v_writelane_b32 v255, s45, 37
	v_writelane_b32 v255, s46, 38
	v_writelane_b32 v255, s47, 39
	v_writelane_b32 v255, s48, 40
	v_writelane_b32 v255, s49, 41
	v_writelane_b32 v255, s50, 42
	v_writelane_b32 v255, s51, 43
	v_writelane_b32 v255, s52, 44
	v_writelane_b32 v255, s53, 45
	v_writelane_b32 v255, s54, 46
	v_writelane_b32 v255, s55, 47
	v_writelane_b32 v255, s56, 48
	v_writelane_b32 v255, s57, 49
	v_writelane_b32 v255, s58, 50
	v_writelane_b32 v255, s59, 51
	v_writelane_b32 v255, s60, 52
	v_writelane_b32 v255, s61, 53
	v_writelane_b32 v255, s62, 54
	v_writelane_b32 v255, s63, 55
	v_writelane_b32 v255, s64, 56
	v_writelane_b32 v255, s65, 57
	v_writelane_b32 v255, s66, 58
	v_writelane_b32 v255, s67, 59
	v_writelane_b32 v255, s68, 60
	v_writelane_b32 v255, s69, 61
	v_writelane_b32 v255, s70, 62
	v_writelane_b32 v255, s71, 63
	v_writelane_b32 v254, s76, 0
	v_writelane_b32 v254, s77, 1
	v_writelane_b32 v254, s80, 2
	v_writelane_b32 v254, s81, 3
	v_writelane_b32 v254, s82, 4
	v_writelane_b32 v254, s83, 5
	v_writelane_b32 v254, s84, 6
	v_writelane_b32 v254, s85, 7
	v_writelane_b32 v254, s86, 8
	v_writelane_b32 v254, s87, 9
	v_writelane_b32 v254, s88, 10
	v_writelane_b32 v254, s89, 11
	v_writelane_b32 v254, s90, 12
	v_writelane_b32 v254, s91, 13
	v_writelane_b32 v254, s92, 14
	v_writelane_b32 v254, s93, 15
	v_writelane_b32 v254, s94, 16
	v_writelane_b32 v254, s95, 17
	v_writelane_b32 v254, s96, 18
	v_writelane_b32 v254, s97, 19
	s_sub_i32 s98, s76, 108
	s_lshl_b32 s98, s98, 3
	s_add_i32 s98, s98, s25
	s_add_i32 s98, s98, 0x6180
	s_movk_i32 s99, 0x4a0
	s_mov_b32 s100, 0x8c80
	s_mov_b32 s101, 1
	s_add_u32 s0, s78, 0xfffffef0
	s_addc_u32 s1, s79, -1
	s_load_dwordx8 s[36:43], s[0:1], 0x40
	s_waitcnt lgkmcnt(0)
	s_branch .Lmy_cvt_entry
.Lmy_back_p2:
	v_readlane_b32 s0, v255, 0
	v_readlane_b32 s1, v255, 1
	v_readlane_b32 s2, v255, 2
	v_readlane_b32 s3, v255, 3
	v_readlane_b32 s4, v255, 4
	v_readlane_b32 s5, v255, 5
	v_readlane_b32 s6, v255, 6
	v_readlane_b32 s7, v255, 7
	v_readlane_b32 s8, v255, 8
	v_readlane_b32 s9, v255, 9
	v_readlane_b32 s10, v255, 10
	v_readlane_b32 s11, v255, 11
	v_readlane_b32 s12, v255, 12
	v_readlane_b32 s13, v255, 13
	v_readlane_b32 s14, v255, 14
	v_readlane_b32 s15, v255, 15
	v_readlane_b32 s16, v255, 16
	v_readlane_b32 s17, v255, 17
	v_readlane_b32 s18, v255, 18
	v_readlane_b32 s19, v255, 19
	v_readlane_b32 s20, v255, 20
	v_readlane_b32 s21, v255, 21
	v_readlane_b32 s22, v255, 22
	v_readlane_b32 s23, v255, 23
	v_readlane_b32 s26, v255, 24
	v_readlane_b32 s27, v255, 25
	v_readlane_b32 s34, v255, 26
	v_readlane_b32 s35, v255, 27
	v_readlane_b32 s36, v255, 28
	v_readlane_b32 s37, v255, 29
	v_readlane_b32 s38, v255, 30
	v_readlane_b32 s39, v255, 31
	v_readlane_b32 s40, v255, 32
	v_readlane_b32 s41, v255, 33
	v_readlane_b32 s42, v255, 34
	v_readlane_b32 s43, v255, 35
	v_readlane_b32 s44, v255, 36
	v_readlane_b32 s45, v255, 37
	v_readlane_b32 s46, v255, 38
	v_readlane_b32 s47, v255, 39
	v_readlane_b32 s48, v255, 40
	v_readlane_b32 s49, v255, 41
	v_readlane_b32 s50, v255, 42
	v_readlane_b32 s51, v255, 43
	v_readlane_b32 s52, v255, 44
	v_readlane_b32 s53, v255, 45
	v_readlane_b32 s54, v255, 46
	v_readlane_b32 s55, v255, 47
	v_readlane_b32 s56, v255, 48
	v_readlane_b32 s57, v255, 49
	v_readlane_b32 s58, v255, 50
	v_readlane_b32 s59, v255, 51
	v_readlane_b32 s60, v255, 52
	v_readlane_b32 s61, v255, 53
	v_readlane_b32 s62, v255, 54
	v_readlane_b32 s63, v255, 55
	v_readlane_b32 s64, v255, 56
	v_readlane_b32 s65, v255, 57
	v_readlane_b32 s66, v255, 58
	v_readlane_b32 s67, v255, 59
	v_readlane_b32 s68, v255, 60
	v_readlane_b32 s69, v255, 61
	v_readlane_b32 s70, v255, 62
	v_readlane_b32 s71, v255, 63
	v_readlane_b32 s76, v254, 0
	v_readlane_b32 s77, v254, 1
	v_readlane_b32 s80, v254, 2
	v_readlane_b32 s81, v254, 3
	v_readlane_b32 s82, v254, 4
	v_readlane_b32 s83, v254, 5
	v_readlane_b32 s84, v254, 6
	v_readlane_b32 s85, v254, 7
	v_readlane_b32 s86, v254, 8
	v_readlane_b32 s87, v254, 9
	v_readlane_b32 s88, v254, 10
	v_readlane_b32 s89, v254, 11
	v_readlane_b32 s90, v254, 12
	v_readlane_b32 s91, v254, 13
	v_readlane_b32 s92, v254, 14
	v_readlane_b32 s93, v254, 15
	v_readlane_b32 s94, v254, 16
	v_readlane_b32 s95, v254, 17
	v_readlane_b32 s96, v254, 18
	v_readlane_b32 s97, v254, 19

.LBB0_716:
	s_waitcnt vmcnt(0)
	s_barrier
	s_cmpk_lg_i32 s33, 0x100
	s_cbranch_scc1 .Lmy_skip_p5
	s_cmp_lt_u32 s76, 164
	s_cbranch_scc1 .Lmy_skip_p5
	s_waitcnt vmcnt(0) lgkmcnt(0)
	s_barrier
	v_writelane_b32 v255, s0, 0
	v_writelane_b32 v255, s1, 1
	v_writelane_b32 v255, s2, 2
	v_writelane_b32 v255, s3, 3
	v_writelane_b32 v255, s4, 4
	v_writelane_b32 v255, s5, 5
	v_writelane_b32 v255, s6, 6
	v_writelane_b32 v255, s7, 7
	v_writelane_b32 v255, s8, 8
	v_writelane_b32 v255, s9, 9
	v_writelane_b32 v255, s10, 10
	v_writelane_b32 v255, s11, 11
	v_writelane_b32 v255, s12, 12
	v_writelane_b32 v255, s13, 13
	v_writelane_b32 v255, s14, 14
	v_writelane_b32 v255, s15, 15
	v_writelane_b32 v255, s16, 16
	v_writelane_b32 v255, s17, 17
	v_writelane_b32 v255, s18, 18
	v_writelane_b32 v255, s19, 19
	v_writelane_b32 v255, s20, 20
	v_writelane_b32 v255, s21, 21
	v_writelane_b32 v255, s22, 22
	v_writelane_b32 v255, s23, 23
	v_writelane_b32 v255, s26, 24
	v_writelane_b32 v255, s27, 25
	v_writelane_b32 v255, s34, 26
	v_writelane_b32 v255, s35, 27
	v_writelane_b32 v255, s36, 28
	v_writelane_b32 v255, s37, 29
	v_writelane_b32 v255, s38, 30
	v_writelane_b32 v255, s39, 31
	v_writelane_b32 v255, s40, 32
	v_writelane_b32 v255, s41, 33
	v_writelane_b32 v255, s42, 34
	v_writelane_b32 v255, s43, 35
	v_writelane_b32 v255, s44, 36
	v_writelane_b32 v255, s45, 37
	v_writelane_b32 v255, s46, 38
	v_writelane_b32 v255, s47, 39
	v_writelane_b32 v255, s48, 40
	v_writelane_b32 v255, s49, 41
	v_writelane_b32 v255, s50, 42
	v_writelane_b32 v255, s51, 43
	v_writelane_b32 v255, s52, 44
	v_writelane_b32 v255, s53, 45
	v_writelane_b32 v255, s54, 46
	v_writelane_b32 v255, s55, 47
	v_writelane_b32 v255, s56, 48
	v_writelane_b32 v255, s57, 49
	v_writelane_b32 v255, s58, 50
	v_writelane_b32 v255, s59, 51
	v_writelane_b32 v255, s60, 52
	v_writelane_b32 v255, s61, 53
	v_writelane_b32 v255, s62, 54
	v_writelane_b32 v255, s63, 55
	v_writelane_b32 v255, s64, 56
	v_writelane_b32 v255, s65, 57
	v_writelane_b32 v255, s66, 58
	v_writelane_b32 v255, s67, 59
	v_writelane_b32 v255, s68, 60
	v_writelane_b32 v255, s69, 61
	v_writelane_b32 v255, s70, 62
	v_writelane_b32 v255, s71, 63
	v_writelane_b32 v254, s76, 0
	v_writelane_b32 v254, s77, 1
	v_writelane_b32 v254, s80, 2
	v_writelane_b32 v254, s81, 3
	v_writelane_b32 v254, s82, 4
	v_writelane_b32 v254, s83, 5
	v_writelane_b32 v254, s84, 6
	v_writelane_b32 v254, s85, 7
	v_writelane_b32 v254, s86, 8
	v_writelane_b32 v254, s87, 9
	v_writelane_b32 v254, s88, 10
	v_writelane_b32 v254, s89, 11
	v_writelane_b32 v254, s90, 12
	v_writelane_b32 v254, s91, 13
	v_writelane_b32 v254, s92, 14
	v_writelane_b32 v254, s93, 15
	v_writelane_b32 v254, s94, 16
	v_writelane_b32 v254, s95, 17
	v_writelane_b32 v254, s96, 18
	v_writelane_b32 v254, s97, 19
	s_sub_i32 s98, s76, 164
	s_lshl_b32 s98, s98, 3
	s_add_i32 s98, s98, s25
	s_add_i32 s98, s98, 0x8c80
	s_movk_i32 s99, 0x2e0
	s_mov_b32 s100, 0xa200
	s_mov_b32 s101, 2
	s_add_u32 s0, s78, 0xfffffef0
	s_addc_u32 s1, s79, -1
	s_load_dwordx8 s[36:43], s[0:1], 0x40
	s_waitcnt lgkmcnt(0)
	s_branch .Lmy_cvt_entry

.Lmy_skip_p5:
	s_cmp_lt_i32 s31, 7
	s_cbranch_scc1 .LBB0_772

.LBB0_893:
	s_branch .Lmy_h1_skip

.Lmy_h1_back:
	s_cmp_eq_u32 s101, 3
	s_cbranch_scc1 .Lmy_back_p11
	s_branch .Lmy_h2_back

.LBB0_1571:
	s_cmpk_lg_i32 s33, 0x100
	s_cbranch_scc1 .Lmy_skip_p11
	s_cmp_lt_u32 s76, 108
	s_cbranch_scc1 .Lmy_skip_p11
	s_waitcnt vmcnt(0) lgkmcnt(0)
	s_barrier
	v_writelane_b32 v255, s0, 0
	v_writelane_b32 v255, s1, 1
	v_writelane_b32 v255, s2, 2
	v_writelane_b32 v255, s3, 3
	v_writelane_b32 v255, s4, 4
	v_writelane_b32 v255, s5, 5
	v_writelane_b32 v255, s6, 6
	v_writelane_b32 v255, s7, 7
	v_writelane_b32 v255, s8, 8
	v_writelane_b32 v255, s9, 9
	v_writelane_b32 v255, s10, 10
	v_writelane_b32 v255, s11, 11
	v_writelane_b32 v255, s12, 12
	v_writelane_b32 v255, s13, 13
	v_writelane_b32 v255, s14, 14
	v_writelane_b32 v255, s15, 15
	v_writelane_b32 v255, s16, 16
	v_writelane_b32 v255, s17, 17
	v_writelane_b32 v255, s18, 18
	v_writelane_b32 v255, s19, 19
	v_writelane_b32 v255, s20, 20
	v_writelane_b32 v255, s21, 21
	v_writelane_b32 v255, s22, 22
	v_writelane_b32 v255, s23, 23
	v_writelane_b32 v255, s26, 24
	v_writelane_b32 v255, s27, 25
	v_writelane_b32 v255, s34, 26
	v_writelane_b32 v255, s35, 27
	v_writelane_b32 v255, s36, 28
	v_writelane_b32 v255, s37, 29
	v_writelane_b32 v255, s38, 30
	v_writelane_b32 v255, s39, 31
	v_writelane_b32 v255, s40, 32
	v_writelane_b32 v255, s41, 33
	v_writelane_b32 v255, s42, 34
	v_writelane_b32 v255, s43, 35
	v_writelane_b32 v255, s44, 36
	v_writelane_b32 v255, s45, 37
	v_writelane_b32 v255, s46, 38
	v_writelane_b32 v255, s47, 39
	v_writelane_b32 v255, s48, 40
	v_writelane_b32 v255, s49, 41
	v_writelane_b32 v255, s50, 42
	v_writelane_b32 v255, s51, 43
	v_writelane_b32 v255, s52, 44
	v_writelane_b32 v255, s53, 45
	v_writelane_b32 v255, s54, 46
	v_writelane_b32 v255, s55, 47
	v_writelane_b32 v255, s56, 48
	v_writelane_b32 v255, s57, 49
	v_writelane_b32 v255, s58, 50
	v_writelane_b32 v255, s59, 51
	v_writelane_b32 v255, s60, 52
	v_writelane_b32 v255, s61, 53
	v_writelane_b32 v255, s62, 54
	v_writelane_b32 v255, s63, 55
	v_writelane_b32 v255, s64, 56
	v_writelane_b32 v255, s65, 57
	v_writelane_b32 v255, s66, 58
	v_writelane_b32 v255, s67, 59
	v_writelane_b32 v255, s68, 60
	v_writelane_b32 v255, s69, 61
	v_writelane_b32 v255, s70, 62
	v_writelane_b32 v255, s71, 63
	v_writelane_b32 v254, s76, 0
	v_writelane_b32 v254, s77, 1
	v_writelane_b32 v254, s80, 2
	v_writelane_b32 v254, s81, 3
	v_writelane_b32 v254, s82, 4
	v_writelane_b32 v254, s83, 5
	v_writelane_b32 v254, s84, 6
	v_writelane_b32 v254, s85, 7
	v_writelane_b32 v254, s86, 8
	v_writelane_b32 v254, s87, 9
	v_writelane_b32 v254, s88, 10
	v_writelane_b32 v254, s89, 11
	v_writelane_b32 v254, s90, 12
	v_writelane_b32 v254, s91, 13
	v_writelane_b32 v254, s92, 14
	v_writelane_b32 v254, s93, 15
	v_writelane_b32 v254, s94, 16
	v_writelane_b32 v254, s95, 17
	v_writelane_b32 v254, s96, 18
	v_writelane_b32 v254, s97, 19
	s_sub_i32 s98, s76, 108
	s_lshl_b32 s98, s98, 3
	s_add_i32 s98, s98, s25
	s_add_i32 s98, s98, 0xa200
	s_movk_i32 s99, 0x4a0
	s_mov_b32 s100, 0xcd00
	s_mov_b32 s101, 3
	s_add_u32 s0, s78, 0xfffffef0
	s_addc_u32 s1, s79, -1
	s_load_dwordx8 s[36:43], s[0:1], 0x40
	s_waitcnt lgkmcnt(0)
	s_branch .Lmy_h1_fwd

.Lmy_h2_back:
	s_cmp_eq_u32 s101, 4
	s_cbranch_scc1 .Lmy_back_p14
	s_branch .Lmy_back_p17

.LBB0_1891:
	s_cmpk_lg_i32 s33, 0x100
	s_cbranch_scc1 .Lmy_skip_p14
	s_cmp_lt_u32 s76, 108
	s_cbranch_scc1 .Lmy_skip_p14
	s_waitcnt vmcnt(0) lgkmcnt(0)
	s_barrier
	v_writelane_b32 v255, s0, 0
	v_writelane_b32 v255, s1, 1
	v_writelane_b32 v255, s2, 2
	v_writelane_b32 v255, s3, 3
	v_writelane_b32 v255, s4, 4
	v_writelane_b32 v255, s5, 5
	v_writelane_b32 v255, s6, 6
	v_writelane_b32 v255, s7, 7
	v_writelane_b32 v255, s8, 8
	v_writelane_b32 v255, s9, 9
	v_writelane_b32 v255, s10, 10
	v_writelane_b32 v255, s11, 11
	v_writelane_b32 v255, s12, 12
	v_writelane_b32 v255, s13, 13
	v_writelane_b32 v255, s14, 14
	v_writelane_b32 v255, s15, 15
	v_writelane_b32 v255, s16, 16
	v_writelane_b32 v255, s17, 17
	v_writelane_b32 v255, s18, 18
	v_writelane_b32 v255, s19, 19
	v_writelane_b32 v255, s20, 20
	v_writelane_b32 v255, s21, 21
	v_writelane_b32 v255, s22, 22
	v_writelane_b32 v255, s23, 23
	v_writelane_b32 v255, s26, 24
	v_writelane_b32 v255, s27, 25
	v_writelane_b32 v255, s34, 26
	v_writelane_b32 v255, s35, 27
	v_writelane_b32 v255, s36, 28
	v_writelane_b32 v255, s37, 29
	v_writelane_b32 v255, s38, 30
	v_writelane_b32 v255, s39, 31
	v_writelane_b32 v255, s40, 32
	v_writelane_b32 v255, s41, 33
	v_writelane_b32 v255, s42, 34
	v_writelane_b32 v255, s43, 35
	v_writelane_b32 v255, s44, 36
	v_writelane_b32 v255, s45, 37
	v_writelane_b32 v255, s46, 38
	v_writelane_b32 v255, s47, 39
	v_writelane_b32 v255, s48, 40
	v_writelane_b32 v255, s49, 41
	v_writelane_b32 v255, s50, 42
	v_writelane_b32 v255, s51, 43
	v_writelane_b32 v255, s52, 44
	v_writelane_b32 v255, s53, 45
	v_writelane_b32 v255, s54, 46
	v_writelane_b32 v255, s55, 47
	v_writelane_b32 v255, s56, 48
	v_writelane_b32 v255, s57, 49
	v_writelane_b32 v255, s58, 50
	v_writelane_b32 v255, s59, 51
	v_writelane_b32 v255, s60, 52
	v_writelane_b32 v255, s61, 53
	v_writelane_b32 v255, s62, 54
	v_writelane_b32 v255, s63, 55
	v_writelane_b32 v255, s64, 56
	v_writelane_b32 v255, s65, 57
	v_writelane_b32 v255, s66, 58
	v_writelane_b32 v255, s67, 59
	v_writelane_b32 v255, s68, 60
	v_writelane_b32 v255, s69, 61
	v_writelane_b32 v255, s70, 62
	v_writelane_b32 v255, s71, 63
	v_writelane_b32 v254, s76, 0
	v_writelane_b32 v254, s77, 1
	v_writelane_b32 v254, s80, 2
	v_writelane_b32 v254, s81, 3
	v_writelane_b32 v254, s82, 4
	v_writelane_b32 v254, s83, 5
	v_writelane_b32 v254, s84, 6
	v_writelane_b32 v254, s85, 7
	v_writelane_b32 v254, s86, 8
	v_writelane_b32 v254, s87, 9
	v_writelane_b32 v254, s88, 10
	v_writelane_b32 v254, s89, 11
	v_writelane_b32 v254, s90, 12
	v_writelane_b32 v254, s91, 13
	v_writelane_b32 v254, s92, 14
	v_writelane_b32 v254, s93, 15
	v_writelane_b32 v254, s94, 16
	v_writelane_b32 v254, s95, 17
	v_writelane_b32 v254, s96, 18
	v_writelane_b32 v254, s97, 19
	s_sub_i32 s98, s76, 108
	s_lshl_b32 s98, s98, 3
	s_add_i32 s98, s98, s25
	s_add_i32 s98, s98, 0xcd00
	s_movk_i32 s99, 0x4a0
	s_mov_b32 s100, 0xfa00
	s_mov_b32 s101, 4
	s_add_u32 s0, s78, 0xfffffef0
	s_addc_u32 s1, s79, -1
	s_load_dwordx8 s[36:43], s[0:1], 0x40
	s_waitcnt lgkmcnt(0)
	s_branch .Lmy_h2_fwd

.LBB0_2241:
	s_waitcnt vmcnt(0)
	s_barrier
	s_cmpk_lg_i32 s33, 0x100
	s_cbranch_scc1 .Lmy_skip_p17
	s_cmp_lt_u32 s76, 48
	s_cbranch_scc1 .Lmy_skip_p17
	s_waitcnt vmcnt(0) lgkmcnt(0)
	s_barrier
	v_writelane_b32 v255, s0, 0
	v_writelane_b32 v255, s1, 1
	v_writelane_b32 v255, s2, 2
	v_writelane_b32 v255, s3, 3
	v_writelane_b32 v255, s4, 4
	v_writelane_b32 v255, s5, 5
	v_writelane_b32 v255, s6, 6
	v_writelane_b32 v255, s7, 7
	v_writelane_b32 v255, s8, 8
	v_writelane_b32 v255, s9, 9
	v_writelane_b32 v255, s10, 10
	v_writelane_b32 v255, s11, 11
	v_writelane_b32 v255, s12, 12
	v_writelane_b32 v255, s13, 13
	v_writelane_b32 v255, s14, 14
	v_writelane_b32 v255, s15, 15
	v_writelane_b32 v255, s16, 16
	v_writelane_b32 v255, s17, 17
	v_writelane_b32 v255, s18, 18
	v_writelane_b32 v255, s19, 19
	v_writelane_b32 v255, s20, 20
	v_writelane_b32 v255, s21, 21
	v_writelane_b32 v255, s22, 22
	v_writelane_b32 v255, s23, 23
	v_writelane_b32 v255, s26, 24
	v_writelane_b32 v255, s27, 25
	v_writelane_b32 v255, s34, 26
	v_writelane_b32 v255, s35, 27
	v_writelane_b32 v255, s36, 28
	v_writelane_b32 v255, s37, 29
	v_writelane_b32 v255, s38, 30
	v_writelane_b32 v255, s39, 31
	v_writelane_b32 v255, s40, 32
	v_writelane_b32 v255, s41, 33
	v_writelane_b32 v255, s42, 34
	v_writelane_b32 v255, s43, 35
	v_writelane_b32 v255, s44, 36
	v_writelane_b32 v255, s45, 37
	v_writelane_b32 v255, s46, 38
	v_writelane_b32 v255, s47, 39
	v_writelane_b32 v255, s48, 40
	v_writelane_b32 v255, s49, 41
	v_writelane_b32 v255, s50, 42
	v_writelane_b32 v255, s51, 43
	v_writelane_b32 v255, s52, 44
	v_writelane_b32 v255, s53, 45
	v_writelane_b32 v255, s54, 46
	v_writelane_b32 v255, s55, 47
	v_writelane_b32 v255, s56, 48
	v_writelane_b32 v255, s57, 49
	v_writelane_b32 v255, s58, 50
	v_writelane_b32 v255, s59, 51
	v_writelane_b32 v255, s60, 52
	v_writelane_b32 v255, s61, 53
	v_writelane_b32 v255, s62, 54
	v_writelane_b32 v255, s63, 55
	v_writelane_b32 v255, s64, 56
	v_writelane_b32 v255, s65, 57
	v_writelane_b32 v255, s66, 58
	v_writelane_b32 v255, s67, 59
	v_writelane_b32 v255, s68, 60
	v_writelane_b32 v255, s69, 61
	v_writelane_b32 v255, s70, 62
	v_writelane_b32 v255, s71, 63
	v_writelane_b32 v254, s76, 0
	v_writelane_b32 v254, s77, 1
	v_writelane_b32 v254, s80, 2
	v_writelane_b32 v254, s81, 3
	v_writelane_b32 v254, s82, 4
	v_writelane_b32 v254, s83, 5
	v_writelane_b32 v254, s84, 6
	v_writelane_b32 v254, s85, 7
	v_writelane_b32 v254, s86, 8
	v_writelane_b32 v254, s87, 9
	v_writelane_b32 v254, s88, 10
	v_writelane_b32 v254, s89, 11
	v_writelane_b32 v254, s90, 12
	v_writelane_b32 v254, s91, 13
	v_writelane_b32 v254, s92, 14
	v_writelane_b32 v254, s93, 15
	v_writelane_b32 v254, s94, 16
	v_writelane_b32 v254, s95, 17
	v_writelane_b32 v254, s96, 18
	v_writelane_b32 v254, s97, 19
	s_sub_i32 s98, s76, 48
	s_lshl_b32 s98, s98, 3
	s_add_i32 s98, s98, s25
	s_add_i32 s98, s98, 0xfa00
	s_movk_i32 s99, 0x680
	s_mov_b32 s100, 0x13a80
	s_mov_b32 s101, 5
	s_add_u32 s0, s78, 0xfffffef0
	s_addc_u32 s1, s79, -1
	s_load_dwordx8 s[36:43], s[0:1], 0x40
	s_waitcnt lgkmcnt(0)
	s_branch .Lmy_h2_fwd

.Lmy_skip_p17:
	s_cmp_lt_i32 s31, 19
	s_cbranch_scc1 .LBB0_2297

	.amdhsa_kernel _Z6mk_fwd4Args
		.amdhsa_group_segment_fixed_size 0
		.amdhsa_private_segment_fixed_size 0
		.amdhsa_kernarg_size 528
		.amdhsa_user_sgpr_count 2
		.amdhsa_user_sgpr_dispatch_ptr 0
		.amdhsa_user_sgpr_queue_ptr 0
		.amdhsa_user_sgpr_kernarg_segment_ptr 1
		.amdhsa_user_sgpr_dispatch_id 0
		.amdhsa_user_sgpr_kernarg_preload_length 0
		.amdhsa_user_sgpr_kernarg_preload_offset 0
		.amdhsa_user_sgpr_private_segment_size 0
		.amdhsa_uses_dynamic_stack 0
		.amdhsa_enable_private_segment 0
		.amdhsa_system_sgpr_workgroup_id_x 1
		.amdhsa_system_sgpr_workgroup_id_y 0
		.amdhsa_system_sgpr_workgroup_id_z 0
		.amdhsa_system_sgpr_workgroup_info 0
		.amdhsa_system_vgpr_workitem_id 0
		.amdhsa_next_free_vgpr 256
		.amdhsa_next_free_sgpr 102
		.amdhsa_accum_offset 256
		.amdhsa_reserve_vcc 1
		.amdhsa_float_round_mode_32 0
		.amdhsa_float_round_mode_16_64 0
		.amdhsa_float_denorm_mode_32 3
		.amdhsa_float_denorm_mode_16_64 3
		.amdhsa_dx10_clamp 1
		.amdhsa_ieee_mode 1
		.amdhsa_fp16_overflow 0
		.amdhsa_tg_split 0
		.amdhsa_exception_fp_ieee_invalid_op 0
		.amdhsa_exception_fp_denorm_src 0
		.amdhsa_exception_fp_ieee_div_zero 0
		.amdhsa_exception_fp_ieee_overflow 0
		.amdhsa_exception_fp_ieee_underflow 0
		.amdhsa_exception_fp_ieee_inexact 0
		.amdhsa_exception_int_div_zero 0
	.end_amdhsa_kernel

amdhsa.kernels:
  - .agpr_count:     0
    .args:
      - .offset:         0
        .size:           272
        .value_kind:     by_value
      - .offset:         272
        .size:           4
        .value_kind:     hidden_block_count_x
      - .offset:         276
        .size:           4
        .value_kind:     hidden_block_count_y
      - .offset:         280
        .size:           4
        .value_kind:     hidden_block_count_z
      - .offset:         284
        .size:           2
        .value_kind:     hidden_group_size_x
      - .offset:         286
        .size:           2
        .value_kind:     hidden_group_size_y
      - .offset:         288
        .size:           2
        .value_kind:     hidden_group_size_z
      - .offset:         290
        .size:           2
        .value_kind:     hidden_remainder_x
      - .offset:         292
        .size:           2
        .value_kind:     hidden_remainder_y
      - .offset:         294
        .size:           2
        .value_kind:     hidden_remainder_z
      - .offset:         312
        .size:           8
        .value_kind:     hidden_global_offset_x
      - .offset:         320
        .size:           8
        .value_kind:     hidden_global_offset_y
      - .offset:         328
        .size:           8
        .value_kind:     hidden_global_offset_z
      - .offset:         336
        .size:           2
        .value_kind:     hidden_grid_dims
      - .offset:         392
        .size:           4
        .value_kind:     hidden_dynamic_lds_size
    .group_segment_fixed_size: 0
    .kernarg_segment_align: 8
    .kernarg_segment_size: 528
    .language:       OpenCL C
    .language_version:
      - 2
      - 0
    .max_flat_workgroup_size: 512
    .name:           _Z6mk_fwd4Args
    .private_segment_fixed_size: 0
    .sgpr_count:     108
    .sgpr_spill_count: 55
    .symbol:         _Z6mk_fwd4Args.kd
    .uniform_work_group_size: 1
    .uses_dynamic_stack: false
    .vgpr_count:     256
    .vgpr_spill_count: 0
    .wavefront_size: 64
